# scan loop: next-chunk LDS staging moved from chunk end to after token 12 (writes retire before the barrier), DPP-hazard nops added, in-order lgkmcnt waits
# baseline (speedup 1.0000x reference)
.Lscan_nored_a:
	s_waitcnt lgkmcnt(1)
	v_pk_mul_f32 v[86:87], v[2:3], v[38:39]
	v_pk_mul_f32 v[78:79], v[2:3], v[34:35]
	v_pk_fma_f32 v[86:87], v[4:5], v[40:41], v[86:87]
	v_pk_mul_f32 v[80:81], v[4:5], v[36:37]
	ds_read_b128 v[38:41], v110 offset:4608
	v_add_f32_e32 v90, v86, v87
	v_pk_fma_f32 v[82:83], v[54:55], v[46:47], v[78:79] op_sel_hi:[0,1,1]
	ds_read_b128 v[34:37], v110 offset:512
	v_add_f32_dpp v90, v90, v90 quad_perm:[1,0,3,2] row_mask:0xf bank_mask:0xf bound_ctrl:1
	v_pk_fma_f32 v[84:85], v[54:55], v[48:49], v[80:81] op_sel_hi:[0,1,1]
	ds_read_b128 v[46:49], v110 offset:12800
	v_add_f32_dpp v90, v90, v90 quad_perm:[2,3,0,1] row_mask:0xf bank_mask:0xf bound_ctrl:1
	ds_read_b32 v54, v111 offset:20992
	s_nop 0
	v_add_f32_dpp v90, v90, v90 row_half_mirror row_mask:0xf bank_mask:0xf bound_ctrl:1
	s_nop 0
	s_nop 0
	v_add_f32_dpp v92, v90, v90 row_mirror row_mask:0xf bank_mask:0xf bound_ctrl:1
	v_pk_fma_f32 v[2:3], v[92:93], v[42:43], v[82:83] op_sel_hi:[0,1,1] neg_lo:[1,0,0] neg_hi:[1,0,0]
	v_pk_fma_f32 v[4:5], v[92:93], v[44:45], v[84:85] op_sel_hi:[0,1,1] neg_lo:[1,0,0] neg_hi:[1,0,0]
	ds_read_b128 v[42:45], v110 offset:8704
	v_pk_mul_f32 v[86:87], v[2:3], v[60:61]
	v_pk_mul_f32 v[78:79], v[2:3], v[56:57]
	v_pk_fma_f32 v[86:87], v[4:5], v[62:63], v[86:87]
	v_pk_mul_f32 v[80:81], v[4:5], v[58:59]
	v_pk_mul_f32 v[88:89], v[2:3], v[50:51]
	v_add_f32_e32 v90, v86, v87
	v_pk_fma_f32 v[82:83], v[76:77], v[68:69], v[78:79] op_sel_hi:[0,1,1]
	v_pk_fma_f32 v[88:89], v[4:5], v[52:53], v[88:89]
	v_add_f32_dpp v90, v90, v90 quad_perm:[1,0,3,2] row_mask:0xf bank_mask:0xf bound_ctrl:1
	v_pk_fma_f32 v[84:85], v[76:77], v[70:71], v[80:81] op_sel_hi:[0,1,1]
	ds_read_b128 v[60:63], v110 offset:4864
	v_add_f32_dpp v90, v90, v90 quad_perm:[2,3,0,1] row_mask:0xf bank_mask:0xf bound_ctrl:1
	ds_read_b128 v[56:59], v110 offset:768
	v_add_f32_e32 v94, v88, v89
	v_add_f32_dpp v90, v90, v90 row_half_mirror row_mask:0xf bank_mask:0xf bound_ctrl:1
	ds_read_b128 v[50:53], v110 offset:16896
	ds_read_b128 v[68:71], v110 offset:13056
	v_add_f32_dpp v92, v90, v90 row_mirror row_mask:0xf bank_mask:0xf bound_ctrl:1
	ds_read_b32 v76, v111 offset:21248
	v_pk_fma_f32 v[2:3], v[92:93], v[64:65], v[82:83] op_sel_hi:[0,1,1] neg_lo:[1,0,0] neg_hi:[1,0,0]
	v_pk_fma_f32 v[4:5], v[92:93], v[66:67], v[84:85] op_sel_hi:[0,1,1] neg_lo:[1,0,0] neg_hi:[1,0,0]
	ds_read_b128 v[64:67], v110 offset:8960
	s_waitcnt lgkmcnt(6)
	v_pk_mul_f32 v[86:87], v[2:3], v[38:39]
	v_pk_mul_f32 v[78:79], v[2:3], v[34:35]
	v_pk_fma_f32 v[86:87], v[4:5], v[40:41], v[86:87]
	v_pk_mul_f32 v[80:81], v[4:5], v[36:37]
	v_pk_mul_f32 v[88:89], v[2:3], v[72:73]
	v_add_f32_e32 v90, v86, v87
	v_pk_fma_f32 v[82:83], v[54:55], v[46:47], v[78:79] op_sel_hi:[0,1,1]
	v_pk_fma_f32 v[88:89], v[4:5], v[74:75], v[88:89]
	v_add_f32_dpp v90, v90, v90 quad_perm:[1,0,3,2] row_mask:0xf bank_mask:0xf bound_ctrl:1
	v_pk_fma_f32 v[84:85], v[54:55], v[48:49], v[80:81] op_sel_hi:[0,1,1]
	ds_read_b128 v[38:41], v110 offset:5120
	v_add_f32_dpp v90, v90, v90 quad_perm:[2,3,0,1] row_mask:0xf bank_mask:0xf bound_ctrl:1
	ds_read_b128 v[34:37], v110 offset:1024
	v_add_f32_e32 v95, v88, v89
	v_add_f32_dpp v90, v90, v90 row_half_mirror row_mask:0xf bank_mask:0xf bound_ctrl:1
	ds_read_b128 v[72:75], v110 offset:17152
	ds_read_b128 v[46:49], v110 offset:13312
	v_add_f32_dpp v92, v90, v90 row_mirror row_mask:0xf bank_mask:0xf bound_ctrl:1
	ds_read_b32 v54, v111 offset:21504
	v_pk_fma_f32 v[2:3], v[92:93], v[42:43], v[82:83] op_sel_hi:[0,1,1] neg_lo:[1,0,0] neg_hi:[1,0,0]
	v_pk_fma_f32 v[4:5], v[92:93], v[44:45], v[84:85] op_sel_hi:[0,1,1] neg_lo:[1,0,0] neg_hi:[1,0,0]
	ds_read_b128 v[42:45], v110 offset:9216
	s_waitcnt lgkmcnt(6)
	v_pk_mul_f32 v[86:87], v[2:3], v[60:61]
	v_pk_mul_f32 v[78:79], v[2:3], v[56:57]
	v_pk_fma_f32 v[86:87], v[4:5], v[62:63], v[86:87]
	v_pk_mul_f32 v[80:81], v[4:5], v[58:59]
	v_pk_mul_f32 v[88:89], v[2:3], v[50:51]
	v_add_f32_e32 v90, v86, v87
	v_pk_fma_f32 v[82:83], v[76:77], v[68:69], v[78:79] op_sel_hi:[0,1,1]
	v_pk_fma_f32 v[88:89], v[4:5], v[52:53], v[88:89]
	v_add_f32_dpp v90, v90, v90 quad_perm:[1,0,3,2] row_mask:0xf bank_mask:0xf bound_ctrl:1
	v_pk_fma_f32 v[84:85], v[76:77], v[70:71], v[80:81] op_sel_hi:[0,1,1]
	ds_read_b128 v[60:63], v110 offset:5376
	v_add_f32_dpp v90, v90, v90 quad_perm:[2,3,0,1] row_mask:0xf bank_mask:0xf bound_ctrl:1
	ds_read_b128 v[56:59], v110 offset:1280
	v_add_f32_e32 v96, v88, v89
	v_add_f32_dpp v90, v90, v90 row_half_mirror row_mask:0xf bank_mask:0xf bound_ctrl:1
	ds_read_b128 v[50:53], v110 offset:17408
	ds_read_b128 v[68:71], v110 offset:13568
	v_add_f32_dpp v92, v90, v90 row_mirror row_mask:0xf bank_mask:0xf bound_ctrl:1
	ds_read_b32 v76, v111 offset:21760
	v_pk_fma_f32 v[2:3], v[92:93], v[64:65], v[82:83] op_sel_hi:[0,1,1] neg_lo:[1,0,0] neg_hi:[1,0,0]
	v_pk_fma_f32 v[4:5], v[92:93], v[66:67], v[84:85] op_sel_hi:[0,1,1] neg_lo:[1,0,0] neg_hi:[1,0,0]
	ds_read_b128 v[64:67], v110 offset:9472
	s_waitcnt lgkmcnt(6)
	v_pk_mul_f32 v[86:87], v[2:3], v[38:39]
	v_pk_mul_f32 v[78:79], v[2:3], v[34:35]
	v_pk_fma_f32 v[86:87], v[4:5], v[40:41], v[86:87]
	v_pk_mul_f32 v[80:81], v[4:5], v[36:37]
	v_pk_mul_f32 v[88:89], v[2:3], v[72:73]
	v_add_f32_e32 v90, v86, v87
	v_pk_fma_f32 v[82:83], v[54:55], v[46:47], v[78:79] op_sel_hi:[0,1,1]
	v_pk_fma_f32 v[88:89], v[4:5], v[74:75], v[88:89]
	v_add_f32_dpp v90, v90, v90 quad_perm:[1,0,3,2] row_mask:0xf bank_mask:0xf bound_ctrl:1
	v_pk_fma_f32 v[84:85], v[54:55], v[48:49], v[80:81] op_sel_hi:[0,1,1]
	ds_read_b128 v[38:41], v110 offset:5632
	v_add_f32_dpp v90, v90, v90 quad_perm:[2,3,0,1] row_mask:0xf bank_mask:0xf bound_ctrl:1
	ds_read_b128 v[34:37], v110 offset:1536
	v_add_f32_e32 v97, v88, v89
	v_add_f32_dpp v90, v90, v90 row_half_mirror row_mask:0xf bank_mask:0xf bound_ctrl:1
	ds_read_b128 v[72:75], v110 offset:17664
	ds_read_b128 v[46:49], v110 offset:13824
	v_add_f32_dpp v92, v90, v90 row_mirror row_mask:0xf bank_mask:0xf bound_ctrl:1
	ds_read_b32 v54, v111 offset:22016
	v_pk_fma_f32 v[2:3], v[92:93], v[42:43], v[82:83] op_sel_hi:[0,1,1] neg_lo:[1,0,0] neg_hi:[1,0,0]
	v_pk_fma_f32 v[4:5], v[92:93], v[44:45], v[84:85] op_sel_hi:[0,1,1] neg_lo:[1,0,0] neg_hi:[1,0,0]
	ds_read_b128 v[42:45], v110 offset:9728
	s_waitcnt lgkmcnt(6)
	v_pk_mul_f32 v[86:87], v[2:3], v[60:61]
	v_pk_mul_f32 v[78:79], v[2:3], v[56:57]
	v_pk_fma_f32 v[86:87], v[4:5], v[62:63], v[86:87]
	v_pk_mul_f32 v[80:81], v[4:5], v[58:59]
	v_pk_mul_f32 v[88:89], v[2:3], v[50:51]
	v_add_f32_e32 v90, v86, v87
	v_pk_fma_f32 v[82:83], v[76:77], v[68:69], v[78:79] op_sel_hi:[0,1,1]
	v_pk_fma_f32 v[88:89], v[4:5], v[52:53], v[88:89]
	v_add_f32_dpp v90, v90, v90 quad_perm:[1,0,3,2] row_mask:0xf bank_mask:0xf bound_ctrl:1
	v_pk_fma_f32 v[84:85], v[76:77], v[70:71], v[80:81] op_sel_hi:[0,1,1]
	ds_read_b128 v[60:63], v110 offset:5888
	v_add_f32_dpp v90, v90, v90 quad_perm:[2,3,0,1] row_mask:0xf bank_mask:0xf bound_ctrl:1
	ds_read_b128 v[56:59], v110 offset:1792
	v_add_f32_e32 v98, v88, v89
	v_add_f32_dpp v90, v90, v90 row_half_mirror row_mask:0xf bank_mask:0xf bound_ctrl:1
	ds_read_b128 v[50:53], v110 offset:17920
	ds_read_b128 v[68:71], v110 offset:14080
	v_add_f32_dpp v92, v90, v90 row_mirror row_mask:0xf bank_mask:0xf bound_ctrl:1
	ds_read_b32 v76, v111 offset:22272
	v_pk_fma_f32 v[2:3], v[92:93], v[64:65], v[82:83] op_sel_hi:[0,1,1] neg_lo:[1,0,0] neg_hi:[1,0,0]
	v_pk_fma_f32 v[4:5], v[92:93], v[66:67], v[84:85] op_sel_hi:[0,1,1] neg_lo:[1,0,0] neg_hi:[1,0,0]
	ds_read_b128 v[64:67], v110 offset:9984
	s_waitcnt lgkmcnt(6)
	v_pk_mul_f32 v[86:87], v[2:3], v[38:39]
	v_pk_mul_f32 v[78:79], v[2:3], v[34:35]
	v_pk_fma_f32 v[86:87], v[4:5], v[40:41], v[86:87]
	v_pk_mul_f32 v[80:81], v[4:5], v[36:37]
	v_pk_mul_f32 v[88:89], v[2:3], v[72:73]
	v_add_f32_e32 v90, v86, v87
	v_pk_fma_f32 v[82:83], v[54:55], v[46:47], v[78:79] op_sel_hi:[0,1,1]
	v_pk_fma_f32 v[88:89], v[4:5], v[74:75], v[88:89]
	v_add_f32_dpp v90, v90, v90 quad_perm:[1,0,3,2] row_mask:0xf bank_mask:0xf bound_ctrl:1
	v_pk_fma_f32 v[84:85], v[54:55], v[48:49], v[80:81] op_sel_hi:[0,1,1]
	ds_read_b128 v[38:41], v110 offset:6144
	v_add_f32_dpp v90, v90, v90 quad_perm:[2,3,0,1] row_mask:0xf bank_mask:0xf bound_ctrl:1
	ds_read_b128 v[34:37], v110 offset:2048
	v_add_f32_e32 v99, v88, v89
	v_add_f32_dpp v90, v90, v90 row_half_mirror row_mask:0xf bank_mask:0xf bound_ctrl:1
	ds_read_b128 v[72:75], v110 offset:18176
	ds_read_b128 v[46:49], v110 offset:14336
	v_add_f32_dpp v92, v90, v90 row_mirror row_mask:0xf bank_mask:0xf bound_ctrl:1
	ds_read_b32 v54, v111 offset:22528
	v_pk_fma_f32 v[2:3], v[92:93], v[42:43], v[82:83] op_sel_hi:[0,1,1] neg_lo:[1,0,0] neg_hi:[1,0,0]
	v_pk_fma_f32 v[4:5], v[92:93], v[44:45], v[84:85] op_sel_hi:[0,1,1] neg_lo:[1,0,0] neg_hi:[1,0,0]
	ds_read_b128 v[42:45], v110 offset:10240
	s_waitcnt lgkmcnt(6)
	v_pk_mul_f32 v[86:87], v[2:3], v[60:61]
	v_pk_mul_f32 v[78:79], v[2:3], v[56:57]
	v_pk_fma_f32 v[86:87], v[4:5], v[62:63], v[86:87]
	v_pk_mul_f32 v[80:81], v[4:5], v[58:59]
	v_pk_mul_f32 v[88:89], v[2:3], v[50:51]
	v_add_f32_e32 v90, v86, v87
	v_pk_fma_f32 v[82:83], v[76:77], v[68:69], v[78:79] op_sel_hi:[0,1,1]
	v_pk_fma_f32 v[88:89], v[4:5], v[52:53], v[88:89]
	v_add_f32_dpp v90, v90, v90 quad_perm:[1,0,3,2] row_mask:0xf bank_mask:0xf bound_ctrl:1
	v_pk_fma_f32 v[84:85], v[76:77], v[70:71], v[80:81] op_sel_hi:[0,1,1]
	ds_read_b128 v[60:63], v110 offset:6400
	v_add_f32_dpp v90, v90, v90 quad_perm:[2,3,0,1] row_mask:0xf bank_mask:0xf bound_ctrl:1
	ds_read_b128 v[56:59], v110 offset:2304
	v_add_f32_e32 v100, v88, v89
	v_add_f32_dpp v90, v90, v90 row_half_mirror row_mask:0xf bank_mask:0xf bound_ctrl:1
	ds_read_b128 v[50:53], v110 offset:18432
	ds_read_b128 v[68:71], v110 offset:14592
	v_add_f32_dpp v92, v90, v90 row_mirror row_mask:0xf bank_mask:0xf bound_ctrl:1
	ds_read_b32 v76, v111 offset:22784
	v_pk_fma_f32 v[2:3], v[92:93], v[64:65], v[82:83] op_sel_hi:[0,1,1] neg_lo:[1,0,0] neg_hi:[1,0,0]
	v_pk_fma_f32 v[4:5], v[92:93], v[66:67], v[84:85] op_sel_hi:[0,1,1] neg_lo:[1,0,0] neg_hi:[1,0,0]
	ds_read_b128 v[64:67], v110 offset:10496
	s_waitcnt lgkmcnt(6)
	v_pk_mul_f32 v[86:87], v[2:3], v[38:39]
	v_pk_mul_f32 v[78:79], v[2:3], v[34:35]
	v_pk_fma_f32 v[86:87], v[4:5], v[40:41], v[86:87]
	v_pk_mul_f32 v[80:81], v[4:5], v[36:37]
	v_pk_mul_f32 v[88:89], v[2:3], v[72:73]
	v_add_f32_e32 v90, v86, v87
	v_pk_fma_f32 v[82:83], v[54:55], v[46:47], v[78:79] op_sel_hi:[0,1,1]
	v_pk_fma_f32 v[88:89], v[4:5], v[74:75], v[88:89]
	v_add_f32_dpp v90, v90, v90 quad_perm:[1,0,3,2] row_mask:0xf bank_mask:0xf bound_ctrl:1
	v_pk_fma_f32 v[84:85], v[54:55], v[48:49], v[80:81] op_sel_hi:[0,1,1]
	ds_read_b128 v[38:41], v110 offset:6656
	v_add_f32_dpp v90, v90, v90 quad_perm:[2,3,0,1] row_mask:0xf bank_mask:0xf bound_ctrl:1
	ds_read_b128 v[34:37], v110 offset:2560
	v_add_f32_e32 v101, v88, v89
	v_add_f32_dpp v90, v90, v90 row_half_mirror row_mask:0xf bank_mask:0xf bound_ctrl:1
	ds_read_b128 v[72:75], v110 offset:18688
	ds_read_b128 v[46:49], v110 offset:14848
	v_add_f32_dpp v92, v90, v90 row_mirror row_mask:0xf bank_mask:0xf bound_ctrl:1
	ds_read_b32 v54, v111 offset:23040
	v_pk_fma_f32 v[2:3], v[92:93], v[42:43], v[82:83] op_sel_hi:[0,1,1] neg_lo:[1,0,0] neg_hi:[1,0,0]
	v_pk_fma_f32 v[4:5], v[92:93], v[44:45], v[84:85] op_sel_hi:[0,1,1] neg_lo:[1,0,0] neg_hi:[1,0,0]
	ds_read_b128 v[42:45], v110 offset:10752
	s_waitcnt lgkmcnt(6)
	v_pk_mul_f32 v[86:87], v[2:3], v[60:61]
	v_pk_mul_f32 v[78:79], v[2:3], v[56:57]
	v_pk_fma_f32 v[86:87], v[4:5], v[62:63], v[86:87]
	v_pk_mul_f32 v[80:81], v[4:5], v[58:59]
	v_pk_mul_f32 v[88:89], v[2:3], v[50:51]
	v_add_f32_e32 v90, v86, v87
	v_pk_fma_f32 v[82:83], v[76:77], v[68:69], v[78:79] op_sel_hi:[0,1,1]
	v_pk_fma_f32 v[88:89], v[4:5], v[52:53], v[88:89]
	v_add_f32_dpp v90, v90, v90 quad_perm:[1,0,3,2] row_mask:0xf bank_mask:0xf bound_ctrl:1
	v_pk_fma_f32 v[84:85], v[76:77], v[70:71], v[80:81] op_sel_hi:[0,1,1]
	ds_read_b128 v[60:63], v110 offset:6912
	v_add_f32_dpp v90, v90, v90 quad_perm:[2,3,0,1] row_mask:0xf bank_mask:0xf bound_ctrl:1
	ds_read_b128 v[56:59], v110 offset:2816
	v_add_f32_e32 v102, v88, v89
	v_add_f32_dpp v90, v90, v90 row_half_mirror row_mask:0xf bank_mask:0xf bound_ctrl:1
	ds_read_b128 v[50:53], v110 offset:18944
	ds_read_b128 v[68:71], v110 offset:15104
	v_add_f32_dpp v92, v90, v90 row_mirror row_mask:0xf bank_mask:0xf bound_ctrl:1
	ds_read_b32 v76, v111 offset:23296
	v_pk_fma_f32 v[2:3], v[92:93], v[64:65], v[82:83] op_sel_hi:[0,1,1] neg_lo:[1,0,0] neg_hi:[1,0,0]
	v_pk_fma_f32 v[4:5], v[92:93], v[66:67], v[84:85] op_sel_hi:[0,1,1] neg_lo:[1,0,0] neg_hi:[1,0,0]
	ds_read_b128 v[64:67], v110 offset:11008
	s_waitcnt lgkmcnt(6)
	v_pk_mul_f32 v[86:87], v[2:3], v[38:39]
	v_pk_mul_f32 v[78:79], v[2:3], v[34:35]
	v_pk_fma_f32 v[86:87], v[4:5], v[40:41], v[86:87]
	v_pk_mul_f32 v[80:81], v[4:5], v[36:37]
	v_pk_mul_f32 v[88:89], v[2:3], v[72:73]
	v_add_f32_e32 v90, v86, v87
	v_pk_fma_f32 v[82:83], v[54:55], v[46:47], v[78:79] op_sel_hi:[0,1,1]
	v_pk_fma_f32 v[88:89], v[4:5], v[74:75], v[88:89]
	v_add_f32_dpp v90, v90, v90 quad_perm:[1,0,3,2] row_mask:0xf bank_mask:0xf bound_ctrl:1
	v_pk_fma_f32 v[84:85], v[54:55], v[48:49], v[80:81] op_sel_hi:[0,1,1]
	ds_read_b128 v[38:41], v110 offset:7168
	v_add_f32_dpp v90, v90, v90 quad_perm:[2,3,0,1] row_mask:0xf bank_mask:0xf bound_ctrl:1
	ds_read_b128 v[34:37], v110 offset:3072
	v_add_f32_e32 v103, v88, v89
	v_add_f32_dpp v90, v90, v90 row_half_mirror row_mask:0xf bank_mask:0xf bound_ctrl:1
	ds_read_b128 v[72:75], v110 offset:19200
	ds_read_b128 v[46:49], v110 offset:15360
	v_add_f32_dpp v92, v90, v90 row_mirror row_mask:0xf bank_mask:0xf bound_ctrl:1
	ds_read_b32 v54, v111 offset:23552
	v_pk_fma_f32 v[2:3], v[92:93], v[42:43], v[82:83] op_sel_hi:[0,1,1] neg_lo:[1,0,0] neg_hi:[1,0,0]
	v_pk_fma_f32 v[4:5], v[92:93], v[44:45], v[84:85] op_sel_hi:[0,1,1] neg_lo:[1,0,0] neg_hi:[1,0,0]
	ds_read_b128 v[42:45], v110 offset:11264
	s_waitcnt lgkmcnt(6)
	v_pk_mul_f32 v[86:87], v[2:3], v[60:61]
	v_pk_mul_f32 v[78:79], v[2:3], v[56:57]
	v_pk_fma_f32 v[86:87], v[4:5], v[62:63], v[86:87]
	v_pk_mul_f32 v[80:81], v[4:5], v[58:59]
	v_pk_mul_f32 v[88:89], v[2:3], v[50:51]
	v_add_f32_e32 v90, v86, v87
	v_pk_fma_f32 v[82:83], v[76:77], v[68:69], v[78:79] op_sel_hi:[0,1,1]
	v_pk_fma_f32 v[88:89], v[4:5], v[52:53], v[88:89]
	v_add_f32_dpp v90, v90, v90 quad_perm:[1,0,3,2] row_mask:0xf bank_mask:0xf bound_ctrl:1
	v_pk_fma_f32 v[84:85], v[76:77], v[70:71], v[80:81] op_sel_hi:[0,1,1]
	ds_read_b128 v[60:63], v110 offset:7424
	v_add_f32_dpp v90, v90, v90 quad_perm:[2,3,0,1] row_mask:0xf bank_mask:0xf bound_ctrl:1
	ds_read_b128 v[56:59], v110 offset:3328
	v_add_f32_e32 v104, v88, v89
	v_add_f32_dpp v90, v90, v90 row_half_mirror row_mask:0xf bank_mask:0xf bound_ctrl:1
	ds_read_b128 v[50:53], v110 offset:19456
	ds_read_b128 v[68:71], v110 offset:15616
	v_add_f32_dpp v92, v90, v90 row_mirror row_mask:0xf bank_mask:0xf bound_ctrl:1
	ds_read_b32 v76, v111 offset:23808
	v_pk_fma_f32 v[2:3], v[92:93], v[64:65], v[82:83] op_sel_hi:[0,1,1] neg_lo:[1,0,0] neg_hi:[1,0,0]
	v_pk_fma_f32 v[4:5], v[92:93], v[66:67], v[84:85] op_sel_hi:[0,1,1] neg_lo:[1,0,0] neg_hi:[1,0,0]
	s_waitcnt vmcnt(6)
	v_pk_add_f32 v[122:123], v[150:151], -1.0 op_sel_hi:[1,0]
	v_pk_add_f32 v[124:125], v[152:153], -1.0 op_sel_hi:[1,0]
	v_pk_mul_f32 v[118:119], v[154:155], v[150:151]
	v_pk_fma_f32 v[122:123], v[6:7], v[122:123], 1.0 op_sel_hi:[1,1,0]
	v_pk_fma_f32 v[124:125], v[8:9], v[124:125], 1.0 op_sel_hi:[1,1,0]
	v_pk_mul_f32 v[120:121], v[156:157], v[152:153]
	v_pk_mul_f32 v[122:123], v[138:139], v[122:123]
	v_pk_mul_f32 v[124:125], v[140:141], v[124:125]
	ds_write_b128 v112, v[146:149] offset:0
	ds_write_b128 v112, v[154:157] offset:4096
	ds_write_b128 v112, v[134:137] offset:16384
	ds_write_b128 v112, v[142:145] offset:20480
	ds_write_b128 v112, v[118:121] offset:8192
	ds_write_b128 v112, v[122:125] offset:12288
	ds_read_b128 v[64:67], v110 offset:11520
	s_waitcnt lgkmcnt(10)
	v_pk_mul_f32 v[86:87], v[2:3], v[38:39]
	v_pk_mul_f32 v[78:79], v[2:3], v[34:35]
	v_pk_fma_f32 v[86:87], v[4:5], v[40:41], v[86:87]
	v_pk_mul_f32 v[80:81], v[4:5], v[36:37]
	v_pk_mul_f32 v[88:89], v[2:3], v[72:73]
	v_add_f32_e32 v90, v86, v87
	v_pk_fma_f32 v[82:83], v[54:55], v[46:47], v[78:79] op_sel_hi:[0,1,1]
	v_pk_fma_f32 v[88:89], v[4:5], v[74:75], v[88:89]
	v_add_f32_dpp v90, v90, v90 quad_perm:[1,0,3,2] row_mask:0xf bank_mask:0xf bound_ctrl:1
	v_pk_fma_f32 v[84:85], v[54:55], v[48:49], v[80:81] op_sel_hi:[0,1,1]
	ds_read_b128 v[38:41], v110 offset:7680
	v_add_f32_dpp v90, v90, v90 quad_perm:[2,3,0,1] row_mask:0xf bank_mask:0xf bound_ctrl:1
	ds_read_b128 v[34:37], v110 offset:3584
	v_add_f32_e32 v105, v88, v89
	v_add_f32_dpp v90, v90, v90 row_half_mirror row_mask:0xf bank_mask:0xf bound_ctrl:1
	ds_read_b128 v[72:75], v110 offset:19712
	ds_read_b128 v[46:49], v110 offset:15872
	v_add_f32_dpp v92, v90, v90 row_mirror row_mask:0xf bank_mask:0xf bound_ctrl:1
	ds_read_b32 v54, v111 offset:24064
	v_pk_fma_f32 v[2:3], v[92:93], v[42:43], v[82:83] op_sel_hi:[0,1,1] neg_lo:[1,0,0] neg_hi:[1,0,0]
	v_pk_fma_f32 v[4:5], v[92:93], v[44:45], v[84:85] op_sel_hi:[0,1,1] neg_lo:[1,0,0] neg_hi:[1,0,0]
	ds_read_b128 v[42:45], v110 offset:11776
	s_waitcnt lgkmcnt(6)
	v_pk_mul_f32 v[86:87], v[2:3], v[60:61]
	v_pk_mul_f32 v[78:79], v[2:3], v[56:57]
	v_pk_fma_f32 v[86:87], v[4:5], v[62:63], v[86:87]
	v_pk_mul_f32 v[80:81], v[4:5], v[58:59]
	v_pk_mul_f32 v[88:89], v[2:3], v[50:51]
	v_add_f32_e32 v90, v86, v87
	v_pk_fma_f32 v[82:83], v[76:77], v[68:69], v[78:79] op_sel_hi:[0,1,1]
	v_pk_fma_f32 v[88:89], v[4:5], v[52:53], v[88:89]
	v_add_f32_dpp v90, v90, v90 quad_perm:[1,0,3,2] row_mask:0xf bank_mask:0xf bound_ctrl:1
	v_pk_fma_f32 v[84:85], v[76:77], v[70:71], v[80:81] op_sel_hi:[0,1,1]
	ds_read_b128 v[60:63], v110 offset:7936
	v_add_f32_dpp v90, v90, v90 quad_perm:[2,3,0,1] row_mask:0xf bank_mask:0xf bound_ctrl:1
	ds_read_b128 v[56:59], v110 offset:3840
	v_add_f32_e32 v106, v88, v89
	v_add_f32_dpp v90, v90, v90 row_half_mirror row_mask:0xf bank_mask:0xf bound_ctrl:1
	ds_read_b128 v[50:53], v110 offset:19968
	ds_read_b128 v[68:71], v110 offset:16128
	v_add_f32_dpp v92, v90, v90 row_mirror row_mask:0xf bank_mask:0xf bound_ctrl:1
	ds_read_b32 v76, v111 offset:24320
	s_cmpk_eq_i32 s33, 0x10f
	s_cbranch_scc1 .Lscan_tail_last
	v_pk_fma_f32 v[2:3], v[92:93], v[64:65], v[82:83] op_sel_hi:[0,1,1] neg_lo:[1,0,0] neg_hi:[1,0,0]
	v_pk_fma_f32 v[4:5], v[92:93], v[66:67], v[84:85] op_sel_hi:[0,1,1] neg_lo:[1,0,0] neg_hi:[1,0,0]
	ds_read_b128 v[64:67], v110 offset:12032
	s_waitcnt lgkmcnt(6)
	v_pk_mul_f32 v[86:87], v[2:3], v[38:39]
	v_pk_mul_f32 v[78:79], v[2:3], v[34:35]
	v_pk_fma_f32 v[86:87], v[4:5], v[40:41], v[86:87]
	v_pk_mul_f32 v[80:81], v[4:5], v[36:37]
	v_pk_mul_f32 v[88:89], v[2:3], v[72:73]
	v_add_f32_e32 v90, v86, v87
	v_pk_fma_f32 v[82:83], v[54:55], v[46:47], v[78:79] op_sel_hi:[0,1,1]
	v_pk_fma_f32 v[88:89], v[4:5], v[74:75], v[88:89]
	v_add_f32_dpp v90, v90, v90 quad_perm:[1,0,3,2] row_mask:0xf bank_mask:0xf bound_ctrl:1
	v_pk_fma_f32 v[84:85], v[54:55], v[48:49], v[80:81] op_sel_hi:[0,1,1]
	s_nop 0
	v_add_f32_dpp v90, v90, v90 quad_perm:[2,3,0,1] row_mask:0xf bank_mask:0xf bound_ctrl:1
	v_add_f32_e32 v107, v88, v89
	s_nop 0
	v_add_f32_dpp v90, v90, v90 row_half_mirror row_mask:0xf bank_mask:0xf bound_ctrl:1
	ds_read_b128 v[72:75], v110 offset:20224
	s_nop 0
	v_add_f32_dpp v92, v90, v90 row_mirror row_mask:0xf bank_mask:0xf bound_ctrl:1
	v_pk_fma_f32 v[2:3], v[92:93], v[42:43], v[82:83] op_sel_hi:[0,1,1] neg_lo:[1,0,0] neg_hi:[1,0,0]
	v_pk_fma_f32 v[4:5], v[92:93], v[44:45], v[84:85] op_sel_hi:[0,1,1] neg_lo:[1,0,0] neg_hi:[1,0,0]
	s_waitcnt lgkmcnt(2)
	v_pk_mul_f32 v[86:87], v[2:3], v[60:61]
	v_pk_mul_f32 v[78:79], v[2:3], v[56:57]
	v_pk_fma_f32 v[86:87], v[4:5], v[62:63], v[86:87]
	v_pk_mul_f32 v[80:81], v[4:5], v[58:59]
	v_pk_mul_f32 v[88:89], v[2:3], v[50:51]
	v_add_f32_e32 v90, v86, v87
	v_pk_fma_f32 v[82:83], v[76:77], v[68:69], v[78:79] op_sel_hi:[0,1,1]
	v_pk_fma_f32 v[88:89], v[4:5], v[52:53], v[88:89]
	v_add_f32_dpp v90, v90, v90 quad_perm:[1,0,3,2] row_mask:0xf bank_mask:0xf bound_ctrl:1
	v_pk_fma_f32 v[84:85], v[76:77], v[70:71], v[80:81] op_sel_hi:[0,1,1]
	s_nop 0
	v_add_f32_dpp v90, v90, v90 quad_perm:[2,3,0,1] row_mask:0xf bank_mask:0xf bound_ctrl:1
	v_add_f32_e32 v108, v88, v89
	s_nop 0
	v_add_f32_dpp v90, v90, v90 row_half_mirror row_mask:0xf bank_mask:0xf bound_ctrl:1
	s_nop 1
	v_add_f32_dpp v92, v90, v90 row_mirror row_mask:0xf bank_mask:0xf bound_ctrl:1
	s_waitcnt lgkmcnt(1)
	v_pk_fma_f32 v[2:3], v[92:93], v[64:65], v[82:83] op_sel_hi:[0,1,1] neg_lo:[1,0,0] neg_hi:[1,0,0]
	v_pk_fma_f32 v[4:5], v[92:93], v[66:67], v[84:85] op_sel_hi:[0,1,1] neg_lo:[1,0,0] neg_hi:[1,0,0]
	s_waitcnt lgkmcnt(0)
	v_pk_mul_f32 v[88:89], v[2:3], v[72:73]
	v_pk_fma_f32 v[88:89], v[4:5], v[74:75], v[88:89]
	v_add_f32_e32 v109, v88, v89
	v_xor_b32_e32 v110, 0x6000, v110
	v_xor_b32_e32 v111, 0x6000, v111
	v_xor_b32_e32 v112, 0x6000, v112
	s_add_i32 s33, s33, 1
	s_waitcnt lgkmcnt(0)
	s_barrier
	ds_read_b128 v[38:41], v110 offset:4096
	ds_read_b128 v[34:37], v110 offset:0
	ds_read_b128 v[46:49], v110 offset:12288
	ds_read_b32 v54, v111 offset:20480
	ds_read_b128 v[42:45], v110 offset:8192
	ds_read_b128 v[50:53], v110 offset:16384
	ds_read_b128 v[60:63], v110 offset:4352
	ds_read_b128 v[56:59], v110 offset:256
	ds_read_b128 v[68:71], v110 offset:12544
	ds_read_b32 v76, v111 offset:20736
	ds_read_b128 v[64:67], v110 offset:8448
	ds_read_b128 v[72:75], v110 offset:16640
	s_cmpk_ge_i32 s33, 0x10e
	s_cbranch_scc1 .Lscan_skipload_b
	v_mul_u32_u24_e32 v0, 0xf00, v113
	v_lshl_add_u32 v125, v113, 10, v115
	v_add_u32_e32 v0, v0, v115
	v_add_u32_e32 v113, s34, v113
	global_load_dwordx4 v[146:149], v125, s[46:47]
	global_load_dwordx4 v[150:153], v125, s[48:49]
	global_load_dwordx4 v[154:157], v125, s[22:23]
	global_load_dwordx4 v[138:141], v0, s[12:13] offset:1024
	global_load_dwordx4 v[134:137], v0, s[12:13]
	global_load_dwordx4 v[142:145], v0, s[12:13] offset:2048
	s_cmp_eq_u32 s33, 13
	s_cbranch_scc0 .Lscan_nogload_b
	v_mov_b32_e32 v113, v117
	s_branch .Lscan_nogload_b

.Lscan_nored_b:
	s_waitcnt lgkmcnt(1)
	v_pk_mul_f32 v[86:87], v[2:3], v[38:39]
	v_pk_mul_f32 v[78:79], v[2:3], v[34:35]
	v_pk_fma_f32 v[86:87], v[4:5], v[40:41], v[86:87]
	v_pk_mul_f32 v[80:81], v[4:5], v[36:37]
	ds_read_b128 v[38:41], v110 offset:4608
	v_add_f32_e32 v90, v86, v87
	v_pk_fma_f32 v[82:83], v[54:55], v[46:47], v[78:79] op_sel_hi:[0,1,1]
	ds_read_b128 v[34:37], v110 offset:512
	v_add_f32_dpp v90, v90, v90 quad_perm:[1,0,3,2] row_mask:0xf bank_mask:0xf bound_ctrl:1
	v_pk_fma_f32 v[84:85], v[54:55], v[48:49], v[80:81] op_sel_hi:[0,1,1]
	ds_read_b128 v[46:49], v110 offset:12800
	v_add_f32_dpp v90, v90, v90 quad_perm:[2,3,0,1] row_mask:0xf bank_mask:0xf bound_ctrl:1
	ds_read_b32 v54, v111 offset:20992
	s_nop 0
	v_add_f32_dpp v90, v90, v90 row_half_mirror row_mask:0xf bank_mask:0xf bound_ctrl:1
	s_nop 0
	s_nop 0
	v_add_f32_dpp v92, v90, v90 row_mirror row_mask:0xf bank_mask:0xf bound_ctrl:1
	v_pk_fma_f32 v[2:3], v[92:93], v[42:43], v[82:83] op_sel_hi:[0,1,1] neg_lo:[1,0,0] neg_hi:[1,0,0]
	v_pk_fma_f32 v[4:5], v[92:93], v[44:45], v[84:85] op_sel_hi:[0,1,1] neg_lo:[1,0,0] neg_hi:[1,0,0]
	ds_read_b128 v[42:45], v110 offset:8704
	v_pk_mul_f32 v[86:87], v[2:3], v[60:61]
	v_pk_mul_f32 v[78:79], v[2:3], v[56:57]
	v_pk_fma_f32 v[86:87], v[4:5], v[62:63], v[86:87]
	v_pk_mul_f32 v[80:81], v[4:5], v[58:59]
	v_pk_mul_f32 v[88:89], v[2:3], v[50:51]
	v_add_f32_e32 v90, v86, v87
	v_pk_fma_f32 v[82:83], v[76:77], v[68:69], v[78:79] op_sel_hi:[0,1,1]
	v_pk_fma_f32 v[88:89], v[4:5], v[52:53], v[88:89]
	v_add_f32_dpp v90, v90, v90 quad_perm:[1,0,3,2] row_mask:0xf bank_mask:0xf bound_ctrl:1
	v_pk_fma_f32 v[84:85], v[76:77], v[70:71], v[80:81] op_sel_hi:[0,1,1]
	ds_read_b128 v[60:63], v110 offset:4864
	v_add_f32_dpp v90, v90, v90 quad_perm:[2,3,0,1] row_mask:0xf bank_mask:0xf bound_ctrl:1
	ds_read_b128 v[56:59], v110 offset:768
	v_add_f32_e32 v94, v88, v89
	v_add_f32_dpp v90, v90, v90 row_half_mirror row_mask:0xf bank_mask:0xf bound_ctrl:1
	ds_read_b128 v[50:53], v110 offset:16896
	ds_read_b128 v[68:71], v110 offset:13056
	v_add_f32_dpp v92, v90, v90 row_mirror row_mask:0xf bank_mask:0xf bound_ctrl:1
	ds_read_b32 v76, v111 offset:21248
	v_pk_fma_f32 v[2:3], v[92:93], v[64:65], v[82:83] op_sel_hi:[0,1,1] neg_lo:[1,0,0] neg_hi:[1,0,0]
	v_pk_fma_f32 v[4:5], v[92:93], v[66:67], v[84:85] op_sel_hi:[0,1,1] neg_lo:[1,0,0] neg_hi:[1,0,0]
	ds_read_b128 v[64:67], v110 offset:8960
	s_waitcnt lgkmcnt(6)
	v_pk_mul_f32 v[86:87], v[2:3], v[38:39]
	v_pk_mul_f32 v[78:79], v[2:3], v[34:35]
	v_pk_fma_f32 v[86:87], v[4:5], v[40:41], v[86:87]
	v_pk_mul_f32 v[80:81], v[4:5], v[36:37]
	v_pk_mul_f32 v[88:89], v[2:3], v[72:73]
	v_add_f32_e32 v90, v86, v87
	v_pk_fma_f32 v[82:83], v[54:55], v[46:47], v[78:79] op_sel_hi:[0,1,1]
	v_pk_fma_f32 v[88:89], v[4:5], v[74:75], v[88:89]
	v_add_f32_dpp v90, v90, v90 quad_perm:[1,0,3,2] row_mask:0xf bank_mask:0xf bound_ctrl:1
	v_pk_fma_f32 v[84:85], v[54:55], v[48:49], v[80:81] op_sel_hi:[0,1,1]
	ds_read_b128 v[38:41], v110 offset:5120
	v_add_f32_dpp v90, v90, v90 quad_perm:[2,3,0,1] row_mask:0xf bank_mask:0xf bound_ctrl:1
	ds_read_b128 v[34:37], v110 offset:1024
	v_add_f32_e32 v95, v88, v89
	v_add_f32_dpp v90, v90, v90 row_half_mirror row_mask:0xf bank_mask:0xf bound_ctrl:1
	ds_read_b128 v[72:75], v110 offset:17152
	ds_read_b128 v[46:49], v110 offset:13312
	v_add_f32_dpp v92, v90, v90 row_mirror row_mask:0xf bank_mask:0xf bound_ctrl:1
	ds_read_b32 v54, v111 offset:21504
	v_pk_fma_f32 v[2:3], v[92:93], v[42:43], v[82:83] op_sel_hi:[0,1,1] neg_lo:[1,0,0] neg_hi:[1,0,0]
	v_pk_fma_f32 v[4:5], v[92:93], v[44:45], v[84:85] op_sel_hi:[0,1,1] neg_lo:[1,0,0] neg_hi:[1,0,0]
	ds_read_b128 v[42:45], v110 offset:9216
	s_waitcnt lgkmcnt(6)
	v_pk_mul_f32 v[86:87], v[2:3], v[60:61]
	v_pk_mul_f32 v[78:79], v[2:3], v[56:57]
	v_pk_fma_f32 v[86:87], v[4:5], v[62:63], v[86:87]
	v_pk_mul_f32 v[80:81], v[4:5], v[58:59]
	v_pk_mul_f32 v[88:89], v[2:3], v[50:51]
	v_add_f32_e32 v90, v86, v87
	v_pk_fma_f32 v[82:83], v[76:77], v[68:69], v[78:79] op_sel_hi:[0,1,1]
	v_pk_fma_f32 v[88:89], v[4:5], v[52:53], v[88:89]
	v_add_f32_dpp v90, v90, v90 quad_perm:[1,0,3,2] row_mask:0xf bank_mask:0xf bound_ctrl:1
	v_pk_fma_f32 v[84:85], v[76:77], v[70:71], v[80:81] op_sel_hi:[0,1,1]
	ds_read_b128 v[60:63], v110 offset:5376
	v_add_f32_dpp v90, v90, v90 quad_perm:[2,3,0,1] row_mask:0xf bank_mask:0xf bound_ctrl:1
	ds_read_b128 v[56:59], v110 offset:1280
	v_add_f32_e32 v96, v88, v89
	v_add_f32_dpp v90, v90, v90 row_half_mirror row_mask:0xf bank_mask:0xf bound_ctrl:1
	ds_read_b128 v[50:53], v110 offset:17408
	ds_read_b128 v[68:71], v110 offset:13568
	v_add_f32_dpp v92, v90, v90 row_mirror row_mask:0xf bank_mask:0xf bound_ctrl:1
	ds_read_b32 v76, v111 offset:21760
	v_pk_fma_f32 v[2:3], v[92:93], v[64:65], v[82:83] op_sel_hi:[0,1,1] neg_lo:[1,0,0] neg_hi:[1,0,0]
	v_pk_fma_f32 v[4:5], v[92:93], v[66:67], v[84:85] op_sel_hi:[0,1,1] neg_lo:[1,0,0] neg_hi:[1,0,0]
	ds_read_b128 v[64:67], v110 offset:9472
	s_waitcnt lgkmcnt(6)
	v_pk_mul_f32 v[86:87], v[2:3], v[38:39]
	v_pk_mul_f32 v[78:79], v[2:3], v[34:35]
	v_pk_fma_f32 v[86:87], v[4:5], v[40:41], v[86:87]
	v_pk_mul_f32 v[80:81], v[4:5], v[36:37]
	v_pk_mul_f32 v[88:89], v[2:3], v[72:73]
	v_add_f32_e32 v90, v86, v87
	v_pk_fma_f32 v[82:83], v[54:55], v[46:47], v[78:79] op_sel_hi:[0,1,1]
	v_pk_fma_f32 v[88:89], v[4:5], v[74:75], v[88:89]
	v_add_f32_dpp v90, v90, v90 quad_perm:[1,0,3,2] row_mask:0xf bank_mask:0xf bound_ctrl:1
	v_pk_fma_f32 v[84:85], v[54:55], v[48:49], v[80:81] op_sel_hi:[0,1,1]
	ds_read_b128 v[38:41], v110 offset:5632
	v_add_f32_dpp v90, v90, v90 quad_perm:[2,3,0,1] row_mask:0xf bank_mask:0xf bound_ctrl:1
	ds_read_b128 v[34:37], v110 offset:1536
	v_add_f32_e32 v97, v88, v89
	v_add_f32_dpp v90, v90, v90 row_half_mirror row_mask:0xf bank_mask:0xf bound_ctrl:1
	ds_read_b128 v[72:75], v110 offset:17664
	ds_read_b128 v[46:49], v110 offset:13824
	v_add_f32_dpp v92, v90, v90 row_mirror row_mask:0xf bank_mask:0xf bound_ctrl:1
	ds_read_b32 v54, v111 offset:22016
	v_pk_fma_f32 v[2:3], v[92:93], v[42:43], v[82:83] op_sel_hi:[0,1,1] neg_lo:[1,0,0] neg_hi:[1,0,0]
	v_pk_fma_f32 v[4:5], v[92:93], v[44:45], v[84:85] op_sel_hi:[0,1,1] neg_lo:[1,0,0] neg_hi:[1,0,0]
	ds_read_b128 v[42:45], v110 offset:9728
	s_waitcnt lgkmcnt(6)
	v_pk_mul_f32 v[86:87], v[2:3], v[60:61]
	v_pk_mul_f32 v[78:79], v[2:3], v[56:57]
	v_pk_fma_f32 v[86:87], v[4:5], v[62:63], v[86:87]
	v_pk_mul_f32 v[80:81], v[4:5], v[58:59]
	v_pk_mul_f32 v[88:89], v[2:3], v[50:51]
	v_add_f32_e32 v90, v86, v87
	v_pk_fma_f32 v[82:83], v[76:77], v[68:69], v[78:79] op_sel_hi:[0,1,1]
	v_pk_fma_f32 v[88:89], v[4:5], v[52:53], v[88:89]
	v_add_f32_dpp v90, v90, v90 quad_perm:[1,0,3,2] row_mask:0xf bank_mask:0xf bound_ctrl:1
	v_pk_fma_f32 v[84:85], v[76:77], v[70:71], v[80:81] op_sel_hi:[0,1,1]
	ds_read_b128 v[60:63], v110 offset:5888
	v_add_f32_dpp v90, v90, v90 quad_perm:[2,3,0,1] row_mask:0xf bank_mask:0xf bound_ctrl:1
	ds_read_b128 v[56:59], v110 offset:1792
	v_add_f32_e32 v98, v88, v89
	v_add_f32_dpp v90, v90, v90 row_half_mirror row_mask:0xf bank_mask:0xf bound_ctrl:1
	ds_read_b128 v[50:53], v110 offset:17920
	ds_read_b128 v[68:71], v110 offset:14080
	v_add_f32_dpp v92, v90, v90 row_mirror row_mask:0xf bank_mask:0xf bound_ctrl:1
	ds_read_b32 v76, v111 offset:22272
	v_pk_fma_f32 v[2:3], v[92:93], v[64:65], v[82:83] op_sel_hi:[0,1,1] neg_lo:[1,0,0] neg_hi:[1,0,0]
	v_pk_fma_f32 v[4:5], v[92:93], v[66:67], v[84:85] op_sel_hi:[0,1,1] neg_lo:[1,0,0] neg_hi:[1,0,0]
	ds_read_b128 v[64:67], v110 offset:9984
	s_waitcnt lgkmcnt(6)
	v_pk_mul_f32 v[86:87], v[2:3], v[38:39]
	v_pk_mul_f32 v[78:79], v[2:3], v[34:35]
	v_pk_fma_f32 v[86:87], v[4:5], v[40:41], v[86:87]
	v_pk_mul_f32 v[80:81], v[4:5], v[36:37]
	v_pk_mul_f32 v[88:89], v[2:3], v[72:73]
	v_add_f32_e32 v90, v86, v87
	v_pk_fma_f32 v[82:83], v[54:55], v[46:47], v[78:79] op_sel_hi:[0,1,1]
	v_pk_fma_f32 v[88:89], v[4:5], v[74:75], v[88:89]
	v_add_f32_dpp v90, v90, v90 quad_perm:[1,0,3,2] row_mask:0xf bank_mask:0xf bound_ctrl:1
	v_pk_fma_f32 v[84:85], v[54:55], v[48:49], v[80:81] op_sel_hi:[0,1,1]
	ds_read_b128 v[38:41], v110 offset:6144
	v_add_f32_dpp v90, v90, v90 quad_perm:[2,3,0,1] row_mask:0xf bank_mask:0xf bound_ctrl:1
	ds_read_b128 v[34:37], v110 offset:2048
	v_add_f32_e32 v99, v88, v89
	v_add_f32_dpp v90, v90, v90 row_half_mirror row_mask:0xf bank_mask:0xf bound_ctrl:1
	ds_read_b128 v[72:75], v110 offset:18176
	ds_read_b128 v[46:49], v110 offset:14336
	v_add_f32_dpp v92, v90, v90 row_mirror row_mask:0xf bank_mask:0xf bound_ctrl:1
	ds_read_b32 v54, v111 offset:22528
	v_pk_fma_f32 v[2:3], v[92:93], v[42:43], v[82:83] op_sel_hi:[0,1,1] neg_lo:[1,0,0] neg_hi:[1,0,0]
	v_pk_fma_f32 v[4:5], v[92:93], v[44:45], v[84:85] op_sel_hi:[0,1,1] neg_lo:[1,0,0] neg_hi:[1,0,0]
	ds_read_b128 v[42:45], v110 offset:10240
	s_waitcnt lgkmcnt(6)
	v_pk_mul_f32 v[86:87], v[2:3], v[60:61]
	v_pk_mul_f32 v[78:79], v[2:3], v[56:57]
	v_pk_fma_f32 v[86:87], v[4:5], v[62:63], v[86:87]
	v_pk_mul_f32 v[80:81], v[4:5], v[58:59]
	v_pk_mul_f32 v[88:89], v[2:3], v[50:51]
	v_add_f32_e32 v90, v86, v87
	v_pk_fma_f32 v[82:83], v[76:77], v[68:69], v[78:79] op_sel_hi:[0,1,1]
	v_pk_fma_f32 v[88:89], v[4:5], v[52:53], v[88:89]
	v_add_f32_dpp v90, v90, v90 quad_perm:[1,0,3,2] row_mask:0xf bank_mask:0xf bound_ctrl:1
	v_pk_fma_f32 v[84:85], v[76:77], v[70:71], v[80:81] op_sel_hi:[0,1,1]
	ds_read_b128 v[60:63], v110 offset:6400
	v_add_f32_dpp v90, v90, v90 quad_perm:[2,3,0,1] row_mask:0xf bank_mask:0xf bound_ctrl:1
	ds_read_b128 v[56:59], v110 offset:2304
	v_add_f32_e32 v100, v88, v89
	v_add_f32_dpp v90, v90, v90 row_half_mirror row_mask:0xf bank_mask:0xf bound_ctrl:1
	ds_read_b128 v[50:53], v110 offset:18432
	ds_read_b128 v[68:71], v110 offset:14592
	v_add_f32_dpp v92, v90, v90 row_mirror row_mask:0xf bank_mask:0xf bound_ctrl:1
	ds_read_b32 v76, v111 offset:22784
	v_pk_fma_f32 v[2:3], v[92:93], v[64:65], v[82:83] op_sel_hi:[0,1,1] neg_lo:[1,0,0] neg_hi:[1,0,0]
	v_pk_fma_f32 v[4:5], v[92:93], v[66:67], v[84:85] op_sel_hi:[0,1,1] neg_lo:[1,0,0] neg_hi:[1,0,0]
	ds_read_b128 v[64:67], v110 offset:10496
	s_waitcnt lgkmcnt(6)
	v_pk_mul_f32 v[86:87], v[2:3], v[38:39]
	v_pk_mul_f32 v[78:79], v[2:3], v[34:35]
	v_pk_fma_f32 v[86:87], v[4:5], v[40:41], v[86:87]
	v_pk_mul_f32 v[80:81], v[4:5], v[36:37]
	v_pk_mul_f32 v[88:89], v[2:3], v[72:73]
	v_add_f32_e32 v90, v86, v87
	v_pk_fma_f32 v[82:83], v[54:55], v[46:47], v[78:79] op_sel_hi:[0,1,1]
	v_pk_fma_f32 v[88:89], v[4:5], v[74:75], v[88:89]
	v_add_f32_dpp v90, v90, v90 quad_perm:[1,0,3,2] row_mask:0xf bank_mask:0xf bound_ctrl:1
	v_pk_fma_f32 v[84:85], v[54:55], v[48:49], v[80:81] op_sel_hi:[0,1,1]
	ds_read_b128 v[38:41], v110 offset:6656
	v_add_f32_dpp v90, v90, v90 quad_perm:[2,3,0,1] row_mask:0xf bank_mask:0xf bound_ctrl:1
	ds_read_b128 v[34:37], v110 offset:2560
	v_add_f32_e32 v101, v88, v89
	v_add_f32_dpp v90, v90, v90 row_half_mirror row_mask:0xf bank_mask:0xf bound_ctrl:1
	ds_read_b128 v[72:75], v110 offset:18688
	ds_read_b128 v[46:49], v110 offset:14848
	v_add_f32_dpp v92, v90, v90 row_mirror row_mask:0xf bank_mask:0xf bound_ctrl:1
	ds_read_b32 v54, v111 offset:23040
	v_pk_fma_f32 v[2:3], v[92:93], v[42:43], v[82:83] op_sel_hi:[0,1,1] neg_lo:[1,0,0] neg_hi:[1,0,0]
	v_pk_fma_f32 v[4:5], v[92:93], v[44:45], v[84:85] op_sel_hi:[0,1,1] neg_lo:[1,0,0] neg_hi:[1,0,0]
	ds_read_b128 v[42:45], v110 offset:10752
	s_waitcnt lgkmcnt(6)
	v_pk_mul_f32 v[86:87], v[2:3], v[60:61]
	v_pk_mul_f32 v[78:79], v[2:3], v[56:57]
	v_pk_fma_f32 v[86:87], v[4:5], v[62:63], v[86:87]
	v_pk_mul_f32 v[80:81], v[4:5], v[58:59]
	v_pk_mul_f32 v[88:89], v[2:3], v[50:51]
	v_add_f32_e32 v90, v86, v87
	v_pk_fma_f32 v[82:83], v[76:77], v[68:69], v[78:79] op_sel_hi:[0,1,1]
	v_pk_fma_f32 v[88:89], v[4:5], v[52:53], v[88:89]
	v_add_f32_dpp v90, v90, v90 quad_perm:[1,0,3,2] row_mask:0xf bank_mask:0xf bound_ctrl:1
	v_pk_fma_f32 v[84:85], v[76:77], v[70:71], v[80:81] op_sel_hi:[0,1,1]
	ds_read_b128 v[60:63], v110 offset:6912
	v_add_f32_dpp v90, v90, v90 quad_perm:[2,3,0,1] row_mask:0xf bank_mask:0xf bound_ctrl:1
	ds_read_b128 v[56:59], v110 offset:2816
	v_add_f32_e32 v102, v88, v89
	v_add_f32_dpp v90, v90, v90 row_half_mirror row_mask:0xf bank_mask:0xf bound_ctrl:1
	ds_read_b128 v[50:53], v110 offset:18944
	ds_read_b128 v[68:71], v110 offset:15104
	v_add_f32_dpp v92, v90, v90 row_mirror row_mask:0xf bank_mask:0xf bound_ctrl:1
	ds_read_b32 v76, v111 offset:23296
	v_pk_fma_f32 v[2:3], v[92:93], v[64:65], v[82:83] op_sel_hi:[0,1,1] neg_lo:[1,0,0] neg_hi:[1,0,0]
	v_pk_fma_f32 v[4:5], v[92:93], v[66:67], v[84:85] op_sel_hi:[0,1,1] neg_lo:[1,0,0] neg_hi:[1,0,0]
	ds_read_b128 v[64:67], v110 offset:11008
	s_waitcnt lgkmcnt(6)
	v_pk_mul_f32 v[86:87], v[2:3], v[38:39]
	v_pk_mul_f32 v[78:79], v[2:3], v[34:35]
	v_pk_fma_f32 v[86:87], v[4:5], v[40:41], v[86:87]
	v_pk_mul_f32 v[80:81], v[4:5], v[36:37]
	v_pk_mul_f32 v[88:89], v[2:3], v[72:73]
	v_add_f32_e32 v90, v86, v87
	v_pk_fma_f32 v[82:83], v[54:55], v[46:47], v[78:79] op_sel_hi:[0,1,1]
	v_pk_fma_f32 v[88:89], v[4:5], v[74:75], v[88:89]
	v_add_f32_dpp v90, v90, v90 quad_perm:[1,0,3,2] row_mask:0xf bank_mask:0xf bound_ctrl:1
	v_pk_fma_f32 v[84:85], v[54:55], v[48:49], v[80:81] op_sel_hi:[0,1,1]
	ds_read_b128 v[38:41], v110 offset:7168
	v_add_f32_dpp v90, v90, v90 quad_perm:[2,3,0,1] row_mask:0xf bank_mask:0xf bound_ctrl:1
	ds_read_b128 v[34:37], v110 offset:3072
	v_add_f32_e32 v103, v88, v89
	v_add_f32_dpp v90, v90, v90 row_half_mirror row_mask:0xf bank_mask:0xf bound_ctrl:1
	ds_read_b128 v[72:75], v110 offset:19200
	ds_read_b128 v[46:49], v110 offset:15360
	v_add_f32_dpp v92, v90, v90 row_mirror row_mask:0xf bank_mask:0xf bound_ctrl:1
	ds_read_b32 v54, v111 offset:23552
	v_pk_fma_f32 v[2:3], v[92:93], v[42:43], v[82:83] op_sel_hi:[0,1,1] neg_lo:[1,0,0] neg_hi:[1,0,0]
	v_pk_fma_f32 v[4:5], v[92:93], v[44:45], v[84:85] op_sel_hi:[0,1,1] neg_lo:[1,0,0] neg_hi:[1,0,0]
	ds_read_b128 v[42:45], v110 offset:11264
	s_waitcnt lgkmcnt(6)
	v_pk_mul_f32 v[86:87], v[2:3], v[60:61]
	v_pk_mul_f32 v[78:79], v[2:3], v[56:57]
	v_pk_fma_f32 v[86:87], v[4:5], v[62:63], v[86:87]
	v_pk_mul_f32 v[80:81], v[4:5], v[58:59]
	v_pk_mul_f32 v[88:89], v[2:3], v[50:51]
	v_add_f32_e32 v90, v86, v87
	v_pk_fma_f32 v[82:83], v[76:77], v[68:69], v[78:79] op_sel_hi:[0,1,1]
	v_pk_fma_f32 v[88:89], v[4:5], v[52:53], v[88:89]
	v_add_f32_dpp v90, v90, v90 quad_perm:[1,0,3,2] row_mask:0xf bank_mask:0xf bound_ctrl:1
	v_pk_fma_f32 v[84:85], v[76:77], v[70:71], v[80:81] op_sel_hi:[0,1,1]
	ds_read_b128 v[60:63], v110 offset:7424
	v_add_f32_dpp v90, v90, v90 quad_perm:[2,3,0,1] row_mask:0xf bank_mask:0xf bound_ctrl:1
	ds_read_b128 v[56:59], v110 offset:3328
	v_add_f32_e32 v104, v88, v89
	v_add_f32_dpp v90, v90, v90 row_half_mirror row_mask:0xf bank_mask:0xf bound_ctrl:1
	ds_read_b128 v[50:53], v110 offset:19456
	ds_read_b128 v[68:71], v110 offset:15616
	v_add_f32_dpp v92, v90, v90 row_mirror row_mask:0xf bank_mask:0xf bound_ctrl:1
	ds_read_b32 v76, v111 offset:23808
	v_pk_fma_f32 v[2:3], v[92:93], v[64:65], v[82:83] op_sel_hi:[0,1,1] neg_lo:[1,0,0] neg_hi:[1,0,0]
	v_pk_fma_f32 v[4:5], v[92:93], v[66:67], v[84:85] op_sel_hi:[0,1,1] neg_lo:[1,0,0] neg_hi:[1,0,0]
	s_waitcnt vmcnt(6)
	v_pk_add_f32 v[122:123], v[26:27], -1.0 op_sel_hi:[1,0]
	v_pk_add_f32 v[124:125], v[28:29], -1.0 op_sel_hi:[1,0]
	v_pk_mul_f32 v[118:119], v[30:31], v[26:27]
	v_pk_fma_f32 v[122:123], v[6:7], v[122:123], 1.0 op_sel_hi:[1,1,0]
	v_pk_fma_f32 v[124:125], v[8:9], v[124:125], 1.0 op_sel_hi:[1,1,0]
	v_pk_mul_f32 v[120:121], v[32:33], v[28:29]
	v_pk_mul_f32 v[122:123], v[14:15], v[122:123]
	v_pk_mul_f32 v[124:125], v[16:17], v[124:125]
	ds_write_b128 v112, v[22:25] offset:0
	ds_write_b128 v112, v[30:33] offset:4096
	ds_write_b128 v112, v[10:13] offset:16384
	ds_write_b128 v112, v[18:21] offset:20480
	ds_write_b128 v112, v[118:121] offset:8192
	ds_write_b128 v112, v[122:125] offset:12288
	ds_read_b128 v[64:67], v110 offset:11520
	s_waitcnt lgkmcnt(10)
	v_pk_mul_f32 v[86:87], v[2:3], v[38:39]
	v_pk_mul_f32 v[78:79], v[2:3], v[34:35]
	v_pk_fma_f32 v[86:87], v[4:5], v[40:41], v[86:87]
	v_pk_mul_f32 v[80:81], v[4:5], v[36:37]
	v_pk_mul_f32 v[88:89], v[2:3], v[72:73]
	v_add_f32_e32 v90, v86, v87
	v_pk_fma_f32 v[82:83], v[54:55], v[46:47], v[78:79] op_sel_hi:[0,1,1]
	v_pk_fma_f32 v[88:89], v[4:5], v[74:75], v[88:89]
	v_add_f32_dpp v90, v90, v90 quad_perm:[1,0,3,2] row_mask:0xf bank_mask:0xf bound_ctrl:1
	v_pk_fma_f32 v[84:85], v[54:55], v[48:49], v[80:81] op_sel_hi:[0,1,1]
	ds_read_b128 v[38:41], v110 offset:7680
	v_add_f32_dpp v90, v90, v90 quad_perm:[2,3,0,1] row_mask:0xf bank_mask:0xf bound_ctrl:1
	ds_read_b128 v[34:37], v110 offset:3584
	v_add_f32_e32 v105, v88, v89
	v_add_f32_dpp v90, v90, v90 row_half_mirror row_mask:0xf bank_mask:0xf bound_ctrl:1
	ds_read_b128 v[72:75], v110 offset:19712
	ds_read_b128 v[46:49], v110 offset:15872
	v_add_f32_dpp v92, v90, v90 row_mirror row_mask:0xf bank_mask:0xf bound_ctrl:1
	ds_read_b32 v54, v111 offset:24064
	v_pk_fma_f32 v[2:3], v[92:93], v[42:43], v[82:83] op_sel_hi:[0,1,1] neg_lo:[1,0,0] neg_hi:[1,0,0]
	v_pk_fma_f32 v[4:5], v[92:93], v[44:45], v[84:85] op_sel_hi:[0,1,1] neg_lo:[1,0,0] neg_hi:[1,0,0]
	ds_read_b128 v[42:45], v110 offset:11776
	s_waitcnt lgkmcnt(6)
	v_pk_mul_f32 v[86:87], v[2:3], v[60:61]
	v_pk_mul_f32 v[78:79], v[2:3], v[56:57]
	v_pk_fma_f32 v[86:87], v[4:5], v[62:63], v[86:87]
	v_pk_mul_f32 v[80:81], v[4:5], v[58:59]
	v_pk_mul_f32 v[88:89], v[2:3], v[50:51]
	v_add_f32_e32 v90, v86, v87
	v_pk_fma_f32 v[82:83], v[76:77], v[68:69], v[78:79] op_sel_hi:[0,1,1]
	v_pk_fma_f32 v[88:89], v[4:5], v[52:53], v[88:89]
	v_add_f32_dpp v90, v90, v90 quad_perm:[1,0,3,2] row_mask:0xf bank_mask:0xf bound_ctrl:1
	v_pk_fma_f32 v[84:85], v[76:77], v[70:71], v[80:81] op_sel_hi:[0,1,1]
	ds_read_b128 v[60:63], v110 offset:7936
	v_add_f32_dpp v90, v90, v90 quad_perm:[2,3,0,1] row_mask:0xf bank_mask:0xf bound_ctrl:1
	ds_read_b128 v[56:59], v110 offset:3840
	v_add_f32_e32 v106, v88, v89
	v_add_f32_dpp v90, v90, v90 row_half_mirror row_mask:0xf bank_mask:0xf bound_ctrl:1
	ds_read_b128 v[50:53], v110 offset:19968
	ds_read_b128 v[68:71], v110 offset:16128
	v_add_f32_dpp v92, v90, v90 row_mirror row_mask:0xf bank_mask:0xf bound_ctrl:1
	ds_read_b32 v76, v111 offset:24320
	s_cmpk_eq_i32 s33, 0x10f
	s_cbranch_scc1 .Lscan_tail_last
	v_pk_fma_f32 v[2:3], v[92:93], v[64:65], v[82:83] op_sel_hi:[0,1,1] neg_lo:[1,0,0] neg_hi:[1,0,0]
	v_pk_fma_f32 v[4:5], v[92:93], v[66:67], v[84:85] op_sel_hi:[0,1,1] neg_lo:[1,0,0] neg_hi:[1,0,0]
	ds_read_b128 v[64:67], v110 offset:12032
	s_waitcnt lgkmcnt(6)
	v_pk_mul_f32 v[86:87], v[2:3], v[38:39]
	v_pk_mul_f32 v[78:79], v[2:3], v[34:35]
	v_pk_fma_f32 v[86:87], v[4:5], v[40:41], v[86:87]
	v_pk_mul_f32 v[80:81], v[4:5], v[36:37]
	v_pk_mul_f32 v[88:89], v[2:3], v[72:73]
	v_add_f32_e32 v90, v86, v87
	v_pk_fma_f32 v[82:83], v[54:55], v[46:47], v[78:79] op_sel_hi:[0,1,1]
	v_pk_fma_f32 v[88:89], v[4:5], v[74:75], v[88:89]
	v_add_f32_dpp v90, v90, v90 quad_perm:[1,0,3,2] row_mask:0xf bank_mask:0xf bound_ctrl:1
	v_pk_fma_f32 v[84:85], v[54:55], v[48:49], v[80:81] op_sel_hi:[0,1,1]
	s_nop 0
	v_add_f32_dpp v90, v90, v90 quad_perm:[2,3,0,1] row_mask:0xf bank_mask:0xf bound_ctrl:1
	v_add_f32_e32 v107, v88, v89
	s_nop 0
	v_add_f32_dpp v90, v90, v90 row_half_mirror row_mask:0xf bank_mask:0xf bound_ctrl:1
	ds_read_b128 v[72:75], v110 offset:20224
	s_nop 0
	v_add_f32_dpp v92, v90, v90 row_mirror row_mask:0xf bank_mask:0xf bound_ctrl:1
	v_pk_fma_f32 v[2:3], v[92:93], v[42:43], v[82:83] op_sel_hi:[0,1,1] neg_lo:[1,0,0] neg_hi:[1,0,0]
	v_pk_fma_f32 v[4:5], v[92:93], v[44:45], v[84:85] op_sel_hi:[0,1,1] neg_lo:[1,0,0] neg_hi:[1,0,0]
	s_waitcnt lgkmcnt(2)
	v_pk_mul_f32 v[86:87], v[2:3], v[60:61]
	v_pk_mul_f32 v[78:79], v[2:3], v[56:57]
	v_pk_fma_f32 v[86:87], v[4:5], v[62:63], v[86:87]
	v_pk_mul_f32 v[80:81], v[4:5], v[58:59]
	v_pk_mul_f32 v[88:89], v[2:3], v[50:51]
	v_add_f32_e32 v90, v86, v87
	v_pk_fma_f32 v[82:83], v[76:77], v[68:69], v[78:79] op_sel_hi:[0,1,1]
	v_pk_fma_f32 v[88:89], v[4:5], v[52:53], v[88:89]
	v_add_f32_dpp v90, v90, v90 quad_perm:[1,0,3,2] row_mask:0xf bank_mask:0xf bound_ctrl:1
	v_pk_fma_f32 v[84:85], v[76:77], v[70:71], v[80:81] op_sel_hi:[0,1,1]
	s_nop 0
	v_add_f32_dpp v90, v90, v90 quad_perm:[2,3,0,1] row_mask:0xf bank_mask:0xf bound_ctrl:1
	v_add_f32_e32 v108, v88, v89
	s_nop 0
	v_add_f32_dpp v90, v90, v90 row_half_mirror row_mask:0xf bank_mask:0xf bound_ctrl:1
	s_nop 1
	v_add_f32_dpp v92, v90, v90 row_mirror row_mask:0xf bank_mask:0xf bound_ctrl:1
	s_waitcnt lgkmcnt(1)
	v_pk_fma_f32 v[2:3], v[92:93], v[64:65], v[82:83] op_sel_hi:[0,1,1] neg_lo:[1,0,0] neg_hi:[1,0,0]
	v_pk_fma_f32 v[4:5], v[92:93], v[66:67], v[84:85] op_sel_hi:[0,1,1] neg_lo:[1,0,0] neg_hi:[1,0,0]
	s_waitcnt lgkmcnt(0)
	v_pk_mul_f32 v[88:89], v[2:3], v[72:73]
	v_pk_fma_f32 v[88:89], v[4:5], v[74:75], v[88:89]
	v_add_f32_e32 v109, v88, v89
	v_xor_b32_e32 v110, 0x6000, v110
	v_xor_b32_e32 v111, 0x6000, v111
	v_xor_b32_e32 v112, 0x6000, v112
	s_add_i32 s33, s33, 1
	s_waitcnt lgkmcnt(0)
	s_barrier
	s_branch .Lscan_chunk
